# pipelined weight transposes (3 items of loads in flight, double-buffered LDS) in the in-projection tail
# speedup vs baseline: 1.1258x; 1.0217x over previous
.LBB0_572:
	s_cmpk_gt_i32 s39, 0x7f
	s_cbranch_scc1 .Lptr_entry
	s_add_i32 s0, s39, 0x340
	s_cmpk_lt_i32 s39, 0x80
	s_cselect_b32 s0, s39, s0
	s_cmpk_gt_i32 s0, 0x7f
	s_mov_b64 s[2:3], -1
	s_cbranch_scc0 .LBB0_590

.Lptr_entry:
	v_readlane_b32 s81, v253, 54
	s_cmpk_gt_i32 s39, 0x59f
	s_cbranch_scc1 .LBB0_602
	s_mov_b32 s84, s39
.Lptr_klast:
	s_add_u32 s0, s84, s81
	s_cmpk_gt_u32 s0, 0x59f
	s_cbranch_scc1 .Lptr_kdone
	s_mov_b32 s84, s0
	s_branch .Lptr_klast
.Lptr_kdone:
	v_lshrrev_b32_e32 v112, 4, v1
	v_and_b32_e32 v113, 15, v1
	v_lshlrev_b32_e32 v113, 4, v113
	v_mul_u32_u24_e32 v114, 0x104, v112
	v_add_u32_e32 v114, v114, v113
	v_lshrrev_b32_e32 v116, 3, v1
	v_and_b32_e32 v117, 7, v1
	v_mul_u32_u24_e32 v115, 0x1040, v117
	v_lshl_add_u32 v115, v116, 2, v115
	v_lshlrev_b32_e32 v117, 5, v117
	s_mul_i32 s48, s81, 0
	s_add_u32 s48, s48, s39
	s_min_u32 s48, s48, s84
	s_sub_u32 s0, s48, 0x80
	s_cmpk_lt_u32 s0, 0x80
	s_cbranch_scc1 .Lptr_dec1_br
	s_cmpk_lt_u32 s0, 0x100
	s_cbranch_scc1 .Lptr_dec1_out
	s_cmpk_lt_u32 s0, 0x3c0
	s_cbranch_scc1 .Lptr_dec1_up
	s_sub_u32 s0, s0, 0x3c0
	s_lshr_b32 s2, s0, 4
	s_and_b32 s3, s0, 15
	s_lshl_b32 s12, s2, 19
	s_lshl_b32 s13, s3, 8
	s_add_u32 s12, s12, s13
	s_add_u32 s30, s21, s12
	s_addc_u32 s31, s68, 0
	s_mul_i32 s12, s3, 0x58000
	s_lshl_b32 s13, s2, 8
	s_add_u32 s12, s12, s13
	s_add_u32 s74, s6, s12
	s_addc_u32 s75, s7, 0
	s_movk_i32 s76, 0x1000
	s_movk_i32 s86, 0x1600
	s_branch .Lptr_dec1_done
.Lptr_dec1_br:
	s_lshr_b32 s14, s0, 6
	s_and_b32 s0, s0, 63
	s_lshr_b32 s2, s0, 4
	s_and_b32 s3, s0, 15
	s_lshl_b32 s12, s2, 19
	s_lshl_b32 s13, s3, 8
	s_add_u32 s12, s12, s13
	s_lshl_b32 s13, s14, 21
	s_add_u32 s12, s12, s13
	s_add_u32 s30, s19, s12
	s_addc_u32 s31, s85, 0
	s_mul_i32 s12, s3, 0x30000
	s_lshl_b32 s13, s2, 8
	s_add_u32 s12, s12, s13
	s_lshl_b32 s13, s14, 10
	s_add_u32 s12, s12, s13
	s_add_u32 s74, s90, s12
	s_addc_u32 s75, s91, 0
	s_movk_i32 s76, 0x1000
	s_movk_i32 s86, 0xc00
	s_branch .Lptr_dec1_done
.Lptr_dec1_out:
	s_sub_u32 s0, s0, 0x80
	s_lshr_b32 s2, s0, 4
	s_and_b32 s3, s0, 15
	s_lshl_b32 s12, s2, 19
	s_lshl_b32 s13, s3, 8
	s_add_u32 s12, s12, s13
	s_add_u32 s30, s1, s12
	s_addc_u32 s31, s78, 0
	s_lshl_b32 s12, s3, 17
	s_lshl_b32 s13, s2, 8
	s_add_u32 s12, s12, s13
	s_add_u32 s74, s92, s12
	s_addc_u32 s75, s93, 0
	s_movk_i32 s76, 0x1000
	s_movk_i32 s86, 0x800
	s_branch .Lptr_dec1_done
.Lptr_dec1_up:
	s_sub_u32 s0, s0, 0x100
	s_mul_i32 s2, s0, 0x2e9
	s_lshr_b32 s2, s2, 16
	s_mul_i32 s3, s2, 0x58
	s_sub_u32 s3, s0, s3
	s_lshr_b32 s12, s3, 2
	s_lshl_b32 s12, s12, 7
	s_and_b32 s13, s3, 1
	s_lshl_b32 s13, s13, 6
	s_add_u32 s12, s12, s13
	s_and_b32 s13, s3, 2
	s_mul_i32 s13, s13, 0x580
	s_add_u32 s12, s12, s13
	s_lshl_b32 s12, s12, 2
	s_mul_i32 s13, s2, 0x2c0000
	s_add_u32 s12, s12, s13
	s_add_u32 s30, s69, s12
	s_addc_u32 s31, s77, 0
	s_lshl_b32 s12, s3, 17
	s_lshl_b32 s13, s2, 8
	s_add_u32 s12, s12, s13
	s_add_u32 s74, s94, s12
	s_addc_u32 s75, s95, 0
	s_movk_i32 s76, 0x5800
	s_movk_i32 s86, 0x800
.Lptr_dec1_done:
	v_mul_lo_u32 v123, v112, s76
	v_add_u32_e32 v118, v123, v113
	s_lshl_b32 vcc_lo, s76, 5
	v_add_u32_e32 v119, vcc_lo, v118
	v_add_u32_e32 v120, vcc_lo, v119
	v_add_u32_e32 v121, vcc_lo, v120
	global_load_dwordx4 v[40:43], v118, s[30:31]
	global_load_dwordx4 v[44:47], v119, s[30:31]
	global_load_dwordx4 v[48:51], v120, s[30:31]
	global_load_dwordx4 v[52:55], v121, s[30:31]
	s_mul_i32 s48, s81, 1
	s_add_u32 s48, s48, s39
	s_min_u32 s48, s48, s84
	s_sub_u32 s0, s48, 0x80
	s_cmpk_lt_u32 s0, 0x80
	s_cbranch_scc1 .Lptr_dec2_br
	s_cmpk_lt_u32 s0, 0x100
	s_cbranch_scc1 .Lptr_dec2_out
	s_cmpk_lt_u32 s0, 0x3c0
	s_cbranch_scc1 .Lptr_dec2_up
	s_sub_u32 s0, s0, 0x3c0
	s_lshr_b32 s2, s0, 4
	s_and_b32 s3, s0, 15
	s_lshl_b32 s12, s2, 19
	s_lshl_b32 s13, s3, 8
	s_add_u32 s12, s12, s13
	s_add_u32 s30, s21, s12
	s_addc_u32 s31, s68, 0
	s_mul_i32 s12, s3, 0x58000
	s_lshl_b32 s13, s2, 8
	s_add_u32 s12, s12, s13
	s_add_u32 s74, s6, s12
	s_addc_u32 s75, s7, 0
	s_movk_i32 s76, 0x1000
	s_movk_i32 s86, 0x1600
	s_branch .Lptr_dec2_done

.Lptr_dec2_done:
	v_mul_lo_u32 v123, v112, s76
	v_add_u32_e32 v118, v123, v113
	s_lshl_b32 vcc_lo, s76, 5
	v_add_u32_e32 v119, vcc_lo, v118
	v_add_u32_e32 v120, vcc_lo, v119
	v_add_u32_e32 v121, vcc_lo, v120
	global_load_dwordx4 v[56:59], v118, s[30:31]
	global_load_dwordx4 v[60:63], v119, s[30:31]
	global_load_dwordx4 v[64:67], v120, s[30:31]
	global_load_dwordx4 v[68:71], v121, s[30:31]
	s_mul_i32 s48, s81, 2
	s_add_u32 s48, s48, s39
	s_min_u32 s48, s48, s84
	s_sub_u32 s0, s48, 0x80
	s_cmpk_lt_u32 s0, 0x80
	s_cbranch_scc1 .Lptr_dec3_br
	s_cmpk_lt_u32 s0, 0x100
	s_cbranch_scc1 .Lptr_dec3_out
	s_cmpk_lt_u32 s0, 0x3c0
	s_cbranch_scc1 .Lptr_dec3_up
	s_sub_u32 s0, s0, 0x3c0
	s_lshr_b32 s2, s0, 4
	s_and_b32 s3, s0, 15
	s_lshl_b32 s12, s2, 19
	s_lshl_b32 s13, s3, 8
	s_add_u32 s12, s12, s13
	s_add_u32 s30, s21, s12
	s_addc_u32 s31, s68, 0
	s_mul_i32 s12, s3, 0x58000
	s_lshl_b32 s13, s2, 8
	s_add_u32 s12, s12, s13
	s_add_u32 s74, s6, s12
	s_addc_u32 s75, s7, 0
	s_movk_i32 s76, 0x1000
	s_movk_i32 s86, 0x1600
	s_branch .Lptr_dec3_done

.Lptr_dec3_done:
	v_mul_lo_u32 v123, v112, s76
	v_add_u32_e32 v118, v123, v113
	s_lshl_b32 vcc_lo, s76, 5
	v_add_u32_e32 v119, vcc_lo, v118
	v_add_u32_e32 v120, vcc_lo, v119
	v_add_u32_e32 v121, vcc_lo, v120
	global_load_dwordx4 v[72:75], v118, s[30:31]
	global_load_dwordx4 v[76:79], v119, s[30:31]
	global_load_dwordx4 v[80:83], v120, s[30:31]
	global_load_dwordx4 v[84:87], v121, s[30:31]
	s_waitcnt vmcnt(8)
	ds_write_b32 v114, v40 offset:0
	ds_write_b32 v114, v41 offset:4
	ds_write_b32 v114, v42 offset:8
	ds_write_b32 v114, v43 offset:12
	ds_write_b32 v114, v44 offset:8320
	ds_write_b32 v114, v45 offset:8324
	ds_write_b32 v114, v46 offset:8328
	ds_write_b32 v114, v47 offset:8332
	ds_write_b32 v114, v48 offset:16640
	ds_write_b32 v114, v49 offset:16644
	ds_write_b32 v114, v50 offset:16648
	ds_write_b32 v114, v51 offset:16652
	ds_write_b32 v114, v52 offset:24960
	ds_write_b32 v114, v53 offset:24964
	ds_write_b32 v114, v54 offset:24968
	ds_write_b32 v114, v55 offset:24972
	s_waitcnt lgkmcnt(0)
	s_barrier
	ds_read_b32 v88, v115 offset:0
	ds_read_b32 v89, v115 offset:260
	ds_read_b32 v90, v115 offset:520
	ds_read_b32 v91, v115 offset:780
	ds_read_b32 v92, v115 offset:1040
	ds_read_b32 v93, v115 offset:1300
	ds_read_b32 v94, v115 offset:1560
	ds_read_b32 v95, v115 offset:1820
	ds_read_b32 v96, v115 offset:2080
	ds_read_b32 v97, v115 offset:2340
	ds_read_b32 v98, v115 offset:2600
	ds_read_b32 v99, v115 offset:2860
	ds_read_b32 v100, v115 offset:3120
	ds_read_b32 v101, v115 offset:3380
	ds_read_b32 v102, v115 offset:3640
	ds_read_b32 v103, v115 offset:3900
	s_mul_i32 s48, s81, 0
	s_add_u32 s48, s48, s39
	s_min_u32 s48, s48, s84
	s_sub_u32 s0, s48, 0x80
	s_cmpk_lt_u32 s0, 0x80
	s_cbranch_scc1 .Lptr_dec4_br
	s_cmpk_lt_u32 s0, 0x100
	s_cbranch_scc1 .Lptr_dec4_out
	s_cmpk_lt_u32 s0, 0x3c0
	s_cbranch_scc1 .Lptr_dec4_up
	s_sub_u32 s0, s0, 0x3c0
	s_lshr_b32 s2, s0, 4
	s_and_b32 s3, s0, 15
	s_lshl_b32 s12, s2, 19
	s_lshl_b32 s13, s3, 8
	s_add_u32 s12, s12, s13
	s_add_u32 s30, s21, s12
	s_addc_u32 s31, s68, 0
	s_mul_i32 s12, s3, 0x58000
	s_lshl_b32 s13, s2, 8
	s_add_u32 s12, s12, s13
	s_add_u32 s74, s6, s12
	s_addc_u32 s75, s7, 0
	s_movk_i32 s76, 0x1000
	s_movk_i32 s86, 0x1600
	s_branch .Lptr_dec4_done

.Lptr_dec4_done:
	v_mul_lo_u32 v122, v116, s86
	v_add_u32_e32 v122, v122, v117
	s_waitcnt lgkmcnt(0)
	v_cvt_pk_bf16_f32 v104, v88, v89
	v_cvt_pk_bf16_f32 v105, v90, v91
	v_cvt_pk_bf16_f32 v106, v92, v93
	v_cvt_pk_bf16_f32 v107, v94, v95
	v_cvt_pk_bf16_f32 v108, v96, v97
	v_cvt_pk_bf16_f32 v109, v98, v99
	v_cvt_pk_bf16_f32 v110, v100, v101
	v_cvt_pk_bf16_f32 v111, v102, v103
	global_store_dwordx4 v122, v[104:107], s[74:75]
	global_store_dwordx4 v122, v[108:111], s[74:75] offset:16
	s_nop 1
	s_mul_i32 s48, s81, 3
	s_add_u32 s48, s48, s39
	s_min_u32 s48, s48, s84
	s_sub_u32 s0, s48, 0x80
	s_cmpk_lt_u32 s0, 0x80
	s_cbranch_scc1 .Lptr_dec5_br
	s_cmpk_lt_u32 s0, 0x100
	s_cbranch_scc1 .Lptr_dec5_out
	s_cmpk_lt_u32 s0, 0x3c0
	s_cbranch_scc1 .Lptr_dec5_up
	s_sub_u32 s0, s0, 0x3c0
	s_lshr_b32 s2, s0, 4
	s_and_b32 s3, s0, 15
	s_lshl_b32 s12, s2, 19
	s_lshl_b32 s13, s3, 8
	s_add_u32 s12, s12, s13
	s_add_u32 s30, s21, s12
	s_addc_u32 s31, s68, 0
	s_mul_i32 s12, s3, 0x58000
	s_lshl_b32 s13, s2, 8
	s_add_u32 s12, s12, s13
	s_add_u32 s74, s6, s12
	s_addc_u32 s75, s7, 0
	s_movk_i32 s76, 0x1000
	s_movk_i32 s86, 0x1600
	s_branch .Lptr_dec5_done

.Lptr_dec5_done:
	v_mul_lo_u32 v123, v112, s76
	v_add_u32_e32 v118, v123, v113
	s_lshl_b32 vcc_lo, s76, 5
	v_add_u32_e32 v119, vcc_lo, v118
	v_add_u32_e32 v120, vcc_lo, v119
	v_add_u32_e32 v121, vcc_lo, v120
	global_load_dwordx4 v[40:43], v118, s[30:31]
	global_load_dwordx4 v[44:47], v119, s[30:31]
	global_load_dwordx4 v[48:51], v120, s[30:31]
	global_load_dwordx4 v[52:55], v121, s[30:31]
	s_waitcnt vmcnt(10)
	ds_write_b32 v114, v56 offset:33792
	ds_write_b32 v114, v57 offset:33796
	ds_write_b32 v114, v58 offset:33800
	ds_write_b32 v114, v59 offset:33804
	ds_write_b32 v114, v60 offset:42112
	ds_write_b32 v114, v61 offset:42116
	ds_write_b32 v114, v62 offset:42120
	ds_write_b32 v114, v63 offset:42124
	ds_write_b32 v114, v64 offset:50432
	ds_write_b32 v114, v65 offset:50436
	ds_write_b32 v114, v66 offset:50440
	ds_write_b32 v114, v67 offset:50444
	ds_write_b32 v114, v68 offset:58752
	ds_write_b32 v114, v69 offset:58756
	ds_write_b32 v114, v70 offset:58760
	ds_write_b32 v114, v71 offset:58764
	s_waitcnt lgkmcnt(0)
	s_barrier
	ds_read_b32 v88, v115 offset:33792
	ds_read_b32 v89, v115 offset:34052
	ds_read_b32 v90, v115 offset:34312
	ds_read_b32 v91, v115 offset:34572
	ds_read_b32 v92, v115 offset:34832
	ds_read_b32 v93, v115 offset:35092
	ds_read_b32 v94, v115 offset:35352
	ds_read_b32 v95, v115 offset:35612
	ds_read_b32 v96, v115 offset:35872
	ds_read_b32 v97, v115 offset:36132
	ds_read_b32 v98, v115 offset:36392
	ds_read_b32 v99, v115 offset:36652
	ds_read_b32 v100, v115 offset:36912
	ds_read_b32 v101, v115 offset:37172
	ds_read_b32 v102, v115 offset:37432
	ds_read_b32 v103, v115 offset:37692
	s_mul_i32 s48, s81, 1
	s_add_u32 s48, s48, s39
	s_min_u32 s48, s48, s84
	s_sub_u32 s0, s48, 0x80
	s_cmpk_lt_u32 s0, 0x80
	s_cbranch_scc1 .Lptr_dec6_br
	s_cmpk_lt_u32 s0, 0x100
	s_cbranch_scc1 .Lptr_dec6_out
	s_cmpk_lt_u32 s0, 0x3c0
	s_cbranch_scc1 .Lptr_dec6_up
	s_sub_u32 s0, s0, 0x3c0
	s_lshr_b32 s2, s0, 4
	s_and_b32 s3, s0, 15
	s_lshl_b32 s12, s2, 19
	s_lshl_b32 s13, s3, 8
	s_add_u32 s12, s12, s13
	s_add_u32 s30, s21, s12
	s_addc_u32 s31, s68, 0
	s_mul_i32 s12, s3, 0x58000
	s_lshl_b32 s13, s2, 8
	s_add_u32 s12, s12, s13
	s_add_u32 s74, s6, s12
	s_addc_u32 s75, s7, 0
	s_movk_i32 s76, 0x1000
	s_movk_i32 s86, 0x1600
	s_branch .Lptr_dec6_done

.Lptr_dec6_done:
	v_mul_lo_u32 v122, v116, s86
	v_add_u32_e32 v122, v122, v117
	s_waitcnt lgkmcnt(0)
	v_cvt_pk_bf16_f32 v104, v88, v89
	v_cvt_pk_bf16_f32 v105, v90, v91
	v_cvt_pk_bf16_f32 v106, v92, v93
	v_cvt_pk_bf16_f32 v107, v94, v95
	v_cvt_pk_bf16_f32 v108, v96, v97
	v_cvt_pk_bf16_f32 v109, v98, v99
	v_cvt_pk_bf16_f32 v110, v100, v101
	v_cvt_pk_bf16_f32 v111, v102, v103
	global_store_dwordx4 v122, v[104:107], s[74:75]
	global_store_dwordx4 v122, v[108:111], s[74:75] offset:16
	s_nop 1
	s_mul_i32 s48, s81, 4
	s_add_u32 s48, s48, s39
	s_min_u32 s48, s48, s84
	s_sub_u32 s0, s48, 0x80
	s_cmpk_lt_u32 s0, 0x80
	s_cbranch_scc1 .Lptr_dec7_br
	s_cmpk_lt_u32 s0, 0x100
	s_cbranch_scc1 .Lptr_dec7_out
	s_cmpk_lt_u32 s0, 0x3c0
	s_cbranch_scc1 .Lptr_dec7_up
	s_sub_u32 s0, s0, 0x3c0
	s_lshr_b32 s2, s0, 4
	s_and_b32 s3, s0, 15
	s_lshl_b32 s12, s2, 19
	s_lshl_b32 s13, s3, 8
	s_add_u32 s12, s12, s13
	s_add_u32 s30, s21, s12
	s_addc_u32 s31, s68, 0
	s_mul_i32 s12, s3, 0x58000
	s_lshl_b32 s13, s2, 8
	s_add_u32 s12, s12, s13
	s_add_u32 s74, s6, s12
	s_addc_u32 s75, s7, 0
	s_movk_i32 s76, 0x1000
	s_movk_i32 s86, 0x1600
	s_branch .Lptr_dec7_done

.Lptr_dec7_done:
	v_mul_lo_u32 v123, v112, s76
	v_add_u32_e32 v118, v123, v113
	s_lshl_b32 vcc_lo, s76, 5
	v_add_u32_e32 v119, vcc_lo, v118
	v_add_u32_e32 v120, vcc_lo, v119
	v_add_u32_e32 v121, vcc_lo, v120
	global_load_dwordx4 v[56:59], v118, s[30:31]
	global_load_dwordx4 v[60:63], v119, s[30:31]
	global_load_dwordx4 v[64:67], v120, s[30:31]
	global_load_dwordx4 v[68:71], v121, s[30:31]
	s_waitcnt vmcnt(12)
	ds_write_b32 v114, v72 offset:0
	ds_write_b32 v114, v73 offset:4
	ds_write_b32 v114, v74 offset:8
	ds_write_b32 v114, v75 offset:12
	ds_write_b32 v114, v76 offset:8320
	ds_write_b32 v114, v77 offset:8324
	ds_write_b32 v114, v78 offset:8328
	ds_write_b32 v114, v79 offset:8332
	ds_write_b32 v114, v80 offset:16640
	ds_write_b32 v114, v81 offset:16644
	ds_write_b32 v114, v82 offset:16648
	ds_write_b32 v114, v83 offset:16652
	ds_write_b32 v114, v84 offset:24960
	ds_write_b32 v114, v85 offset:24964
	ds_write_b32 v114, v86 offset:24968
	ds_write_b32 v114, v87 offset:24972
	s_waitcnt lgkmcnt(0)
	s_barrier
	ds_read_b32 v88, v115 offset:0
	ds_read_b32 v89, v115 offset:260
	ds_read_b32 v90, v115 offset:520
	ds_read_b32 v91, v115 offset:780
	ds_read_b32 v92, v115 offset:1040
	ds_read_b32 v93, v115 offset:1300
	ds_read_b32 v94, v115 offset:1560
	ds_read_b32 v95, v115 offset:1820
	ds_read_b32 v96, v115 offset:2080
	ds_read_b32 v97, v115 offset:2340
	ds_read_b32 v98, v115 offset:2600
	ds_read_b32 v99, v115 offset:2860
	ds_read_b32 v100, v115 offset:3120
	ds_read_b32 v101, v115 offset:3380
	ds_read_b32 v102, v115 offset:3640
	ds_read_b32 v103, v115 offset:3900
	s_mul_i32 s48, s81, 2
	s_add_u32 s48, s48, s39
	s_min_u32 s48, s48, s84
	s_sub_u32 s0, s48, 0x80
	s_cmpk_lt_u32 s0, 0x80
	s_cbranch_scc1 .Lptr_dec8_br
	s_cmpk_lt_u32 s0, 0x100
	s_cbranch_scc1 .Lptr_dec8_out
	s_cmpk_lt_u32 s0, 0x3c0
	s_cbranch_scc1 .Lptr_dec8_up
	s_sub_u32 s0, s0, 0x3c0
	s_lshr_b32 s2, s0, 4
	s_and_b32 s3, s0, 15
	s_lshl_b32 s12, s2, 19
	s_lshl_b32 s13, s3, 8
	s_add_u32 s12, s12, s13
	s_add_u32 s30, s21, s12
	s_addc_u32 s31, s68, 0
	s_mul_i32 s12, s3, 0x58000
	s_lshl_b32 s13, s2, 8
	s_add_u32 s12, s12, s13
	s_add_u32 s74, s6, s12
	s_addc_u32 s75, s7, 0
	s_movk_i32 s76, 0x1000
	s_movk_i32 s86, 0x1600
	s_branch .Lptr_dec8_done

.Lptr_dec8_done:
	v_mul_lo_u32 v122, v116, s86
	v_add_u32_e32 v122, v122, v117
	s_waitcnt lgkmcnt(0)
	v_cvt_pk_bf16_f32 v104, v88, v89
	v_cvt_pk_bf16_f32 v105, v90, v91
	v_cvt_pk_bf16_f32 v106, v92, v93
	v_cvt_pk_bf16_f32 v107, v94, v95
	v_cvt_pk_bf16_f32 v108, v96, v97
	v_cvt_pk_bf16_f32 v109, v98, v99
	v_cvt_pk_bf16_f32 v110, v100, v101
	v_cvt_pk_bf16_f32 v111, v102, v103
	global_store_dwordx4 v122, v[104:107], s[74:75]
	global_store_dwordx4 v122, v[108:111], s[74:75] offset:16
	s_nop 1
	s_mul_i32 s48, s81, 5
	s_add_u32 s48, s48, s39
	s_min_u32 s48, s48, s84
	s_sub_u32 s0, s48, 0x80
	s_cmpk_lt_u32 s0, 0x80
	s_cbranch_scc1 .Lptr_dec9_br
	s_cmpk_lt_u32 s0, 0x100
	s_cbranch_scc1 .Lptr_dec9_out
	s_cmpk_lt_u32 s0, 0x3c0
	s_cbranch_scc1 .Lptr_dec9_up
	s_sub_u32 s0, s0, 0x3c0
	s_lshr_b32 s2, s0, 4
	s_and_b32 s3, s0, 15
	s_lshl_b32 s12, s2, 19
	s_lshl_b32 s13, s3, 8
	s_add_u32 s12, s12, s13
	s_add_u32 s30, s21, s12
	s_addc_u32 s31, s68, 0
	s_mul_i32 s12, s3, 0x58000
	s_lshl_b32 s13, s2, 8
	s_add_u32 s12, s12, s13
	s_add_u32 s74, s6, s12
	s_addc_u32 s75, s7, 0
	s_movk_i32 s76, 0x1000
	s_movk_i32 s86, 0x1600
	s_branch .Lptr_dec9_done

.Lptr_dec9_done:
	v_mul_lo_u32 v123, v112, s76
	v_add_u32_e32 v118, v123, v113
	s_lshl_b32 vcc_lo, s76, 5
	v_add_u32_e32 v119, vcc_lo, v118
	v_add_u32_e32 v120, vcc_lo, v119
	v_add_u32_e32 v121, vcc_lo, v120
	global_load_dwordx4 v[72:75], v118, s[30:31]
	global_load_dwordx4 v[76:79], v119, s[30:31]
	global_load_dwordx4 v[80:83], v120, s[30:31]
	global_load_dwordx4 v[84:87], v121, s[30:31]
	s_waitcnt vmcnt(12)
	ds_write_b32 v114, v40 offset:33792
	ds_write_b32 v114, v41 offset:33796
	ds_write_b32 v114, v42 offset:33800
	ds_write_b32 v114, v43 offset:33804
	ds_write_b32 v114, v44 offset:42112
	ds_write_b32 v114, v45 offset:42116
	ds_write_b32 v114, v46 offset:42120
	ds_write_b32 v114, v47 offset:42124
	ds_write_b32 v114, v48 offset:50432
	ds_write_b32 v114, v49 offset:50436
	ds_write_b32 v114, v50 offset:50440
	ds_write_b32 v114, v51 offset:50444
	ds_write_b32 v114, v52 offset:58752
	ds_write_b32 v114, v53 offset:58756
	ds_write_b32 v114, v54 offset:58760
	ds_write_b32 v114, v55 offset:58764
	s_waitcnt lgkmcnt(0)
	s_barrier
	ds_read_b32 v88, v115 offset:33792
	ds_read_b32 v89, v115 offset:34052
	ds_read_b32 v90, v115 offset:34312
	ds_read_b32 v91, v115 offset:34572
	ds_read_b32 v92, v115 offset:34832
	ds_read_b32 v93, v115 offset:35092
	ds_read_b32 v94, v115 offset:35352
	ds_read_b32 v95, v115 offset:35612
	ds_read_b32 v96, v115 offset:35872
	ds_read_b32 v97, v115 offset:36132
	ds_read_b32 v98, v115 offset:36392
	ds_read_b32 v99, v115 offset:36652
	ds_read_b32 v100, v115 offset:36912
	ds_read_b32 v101, v115 offset:37172
	ds_read_b32 v102, v115 offset:37432
	ds_read_b32 v103, v115 offset:37692
	s_mul_i32 s48, s81, 3
	s_add_u32 s48, s48, s39
	s_min_u32 s48, s48, s84
	s_sub_u32 s0, s48, 0x80
	s_cmpk_lt_u32 s0, 0x80
	s_cbranch_scc1 .Lptr_dec10_br
	s_cmpk_lt_u32 s0, 0x100
	s_cbranch_scc1 .Lptr_dec10_out
	s_cmpk_lt_u32 s0, 0x3c0
	s_cbranch_scc1 .Lptr_dec10_up
	s_sub_u32 s0, s0, 0x3c0
	s_lshr_b32 s2, s0, 4
	s_and_b32 s3, s0, 15
	s_lshl_b32 s12, s2, 19
	s_lshl_b32 s13, s3, 8
	s_add_u32 s12, s12, s13
	s_add_u32 s30, s21, s12
	s_addc_u32 s31, s68, 0
	s_mul_i32 s12, s3, 0x58000
	s_lshl_b32 s13, s2, 8
	s_add_u32 s12, s12, s13
	s_add_u32 s74, s6, s12
	s_addc_u32 s75, s7, 0
	s_movk_i32 s76, 0x1000
	s_movk_i32 s86, 0x1600
	s_branch .Lptr_dec10_done

.Lptr_dec10_done:
	v_mul_lo_u32 v122, v116, s86
	v_add_u32_e32 v122, v122, v117
	s_waitcnt lgkmcnt(0)
	v_cvt_pk_bf16_f32 v104, v88, v89
	v_cvt_pk_bf16_f32 v105, v90, v91
	v_cvt_pk_bf16_f32 v106, v92, v93
	v_cvt_pk_bf16_f32 v107, v94, v95
	v_cvt_pk_bf16_f32 v108, v96, v97
	v_cvt_pk_bf16_f32 v109, v98, v99
	v_cvt_pk_bf16_f32 v110, v100, v101
	v_cvt_pk_bf16_f32 v111, v102, v103
	global_store_dwordx4 v122, v[104:107], s[74:75]
	global_store_dwordx4 v122, v[108:111], s[74:75] offset:16
	s_nop 1
	s_mul_i32 s48, s81, 6
	s_add_u32 s48, s48, s39
	s_min_u32 s48, s48, s84
	s_sub_u32 s0, s48, 0x80
	s_cmpk_lt_u32 s0, 0x80
	s_cbranch_scc1 .Lptr_dec11_br
	s_cmpk_lt_u32 s0, 0x100
	s_cbranch_scc1 .Lptr_dec11_out
	s_cmpk_lt_u32 s0, 0x3c0
	s_cbranch_scc1 .Lptr_dec11_up
	s_sub_u32 s0, s0, 0x3c0
	s_lshr_b32 s2, s0, 4
	s_and_b32 s3, s0, 15
	s_lshl_b32 s12, s2, 19
	s_lshl_b32 s13, s3, 8
	s_add_u32 s12, s12, s13
	s_add_u32 s30, s21, s12
	s_addc_u32 s31, s68, 0
	s_mul_i32 s12, s3, 0x58000
	s_lshl_b32 s13, s2, 8
	s_add_u32 s12, s12, s13
	s_add_u32 s74, s6, s12
	s_addc_u32 s75, s7, 0
	s_movk_i32 s76, 0x1000
	s_movk_i32 s86, 0x1600
	s_branch .Lptr_dec11_done

.Lptr_dec11_done:
	v_mul_lo_u32 v123, v112, s76
	v_add_u32_e32 v118, v123, v113
	s_lshl_b32 vcc_lo, s76, 5
	v_add_u32_e32 v119, vcc_lo, v118
	v_add_u32_e32 v120, vcc_lo, v119
	v_add_u32_e32 v121, vcc_lo, v120
	global_load_dwordx4 v[40:43], v118, s[30:31]
	global_load_dwordx4 v[44:47], v119, s[30:31]
	global_load_dwordx4 v[48:51], v120, s[30:31]
	global_load_dwordx4 v[52:55], v121, s[30:31]
	s_waitcnt vmcnt(12)
	ds_write_b32 v114, v56 offset:0
	ds_write_b32 v114, v57 offset:4
	ds_write_b32 v114, v58 offset:8
	ds_write_b32 v114, v59 offset:12
	ds_write_b32 v114, v60 offset:8320
	ds_write_b32 v114, v61 offset:8324
	ds_write_b32 v114, v62 offset:8328
	ds_write_b32 v114, v63 offset:8332
	ds_write_b32 v114, v64 offset:16640
	ds_write_b32 v114, v65 offset:16644
	ds_write_b32 v114, v66 offset:16648
	ds_write_b32 v114, v67 offset:16652
	ds_write_b32 v114, v68 offset:24960
	ds_write_b32 v114, v69 offset:24964
	ds_write_b32 v114, v70 offset:24968
	ds_write_b32 v114, v71 offset:24972
	s_waitcnt lgkmcnt(0)
	s_barrier
	ds_read_b32 v88, v115 offset:0
	ds_read_b32 v89, v115 offset:260
	ds_read_b32 v90, v115 offset:520
	ds_read_b32 v91, v115 offset:780
	ds_read_b32 v92, v115 offset:1040
	ds_read_b32 v93, v115 offset:1300
	ds_read_b32 v94, v115 offset:1560
	ds_read_b32 v95, v115 offset:1820
	ds_read_b32 v96, v115 offset:2080
	ds_read_b32 v97, v115 offset:2340
	ds_read_b32 v98, v115 offset:2600
	ds_read_b32 v99, v115 offset:2860
	ds_read_b32 v100, v115 offset:3120
	ds_read_b32 v101, v115 offset:3380
	ds_read_b32 v102, v115 offset:3640
	ds_read_b32 v103, v115 offset:3900
	s_mul_i32 s48, s81, 4
	s_add_u32 s48, s48, s39
	s_min_u32 s48, s48, s84
	s_sub_u32 s0, s48, 0x80
	s_cmpk_lt_u32 s0, 0x80
	s_cbranch_scc1 .Lptr_dec12_br
	s_cmpk_lt_u32 s0, 0x100
	s_cbranch_scc1 .Lptr_dec12_out
	s_cmpk_lt_u32 s0, 0x3c0
	s_cbranch_scc1 .Lptr_dec12_up
	s_sub_u32 s0, s0, 0x3c0
	s_lshr_b32 s2, s0, 4
	s_and_b32 s3, s0, 15
	s_lshl_b32 s12, s2, 19
	s_lshl_b32 s13, s3, 8
	s_add_u32 s12, s12, s13
	s_add_u32 s30, s21, s12
	s_addc_u32 s31, s68, 0
	s_mul_i32 s12, s3, 0x58000
	s_lshl_b32 s13, s2, 8
	s_add_u32 s12, s12, s13
	s_add_u32 s74, s6, s12
	s_addc_u32 s75, s7, 0
	s_movk_i32 s76, 0x1000
	s_movk_i32 s86, 0x1600
	s_branch .Lptr_dec12_done

.Lptr_dec12_done:
	v_mul_lo_u32 v122, v116, s86
	v_add_u32_e32 v122, v122, v117
	s_waitcnt lgkmcnt(0)
	v_cvt_pk_bf16_f32 v104, v88, v89
	v_cvt_pk_bf16_f32 v105, v90, v91
	v_cvt_pk_bf16_f32 v106, v92, v93
	v_cvt_pk_bf16_f32 v107, v94, v95
	v_cvt_pk_bf16_f32 v108, v96, v97
	v_cvt_pk_bf16_f32 v109, v98, v99
	v_cvt_pk_bf16_f32 v110, v100, v101
	v_cvt_pk_bf16_f32 v111, v102, v103
	global_store_dwordx4 v122, v[104:107], s[74:75]
	global_store_dwordx4 v122, v[108:111], s[74:75] offset:16
	s_nop 1
	s_waitcnt vmcnt(8)
	ds_write_b32 v114, v72 offset:33792
	ds_write_b32 v114, v73 offset:33796
	ds_write_b32 v114, v74 offset:33800
	ds_write_b32 v114, v75 offset:33804
	ds_write_b32 v114, v76 offset:42112
	ds_write_b32 v114, v77 offset:42116
	ds_write_b32 v114, v78 offset:42120
	ds_write_b32 v114, v79 offset:42124
	ds_write_b32 v114, v80 offset:50432
	ds_write_b32 v114, v81 offset:50436
	ds_write_b32 v114, v82 offset:50440
	ds_write_b32 v114, v83 offset:50444
	ds_write_b32 v114, v84 offset:58752
	ds_write_b32 v114, v85 offset:58756
	ds_write_b32 v114, v86 offset:58760
	ds_write_b32 v114, v87 offset:58764
	s_waitcnt lgkmcnt(0)
	s_barrier
	ds_read_b32 v88, v115 offset:33792
	ds_read_b32 v89, v115 offset:34052
	ds_read_b32 v90, v115 offset:34312
	ds_read_b32 v91, v115 offset:34572
	ds_read_b32 v92, v115 offset:34832
	ds_read_b32 v93, v115 offset:35092
	ds_read_b32 v94, v115 offset:35352
	ds_read_b32 v95, v115 offset:35612
	ds_read_b32 v96, v115 offset:35872
	ds_read_b32 v97, v115 offset:36132
	ds_read_b32 v98, v115 offset:36392
	ds_read_b32 v99, v115 offset:36652
	ds_read_b32 v100, v115 offset:36912
	ds_read_b32 v101, v115 offset:37172
	ds_read_b32 v102, v115 offset:37432
	ds_read_b32 v103, v115 offset:37692
	s_mul_i32 s48, s81, 5
	s_add_u32 s48, s48, s39
	s_min_u32 s48, s48, s84
	s_sub_u32 s0, s48, 0x80
	s_cmpk_lt_u32 s0, 0x80
	s_cbranch_scc1 .Lptr_dec13_br
	s_cmpk_lt_u32 s0, 0x100
	s_cbranch_scc1 .Lptr_dec13_out
	s_cmpk_lt_u32 s0, 0x3c0
	s_cbranch_scc1 .Lptr_dec13_up
	s_sub_u32 s0, s0, 0x3c0
	s_lshr_b32 s2, s0, 4
	s_and_b32 s3, s0, 15
	s_lshl_b32 s12, s2, 19
	s_lshl_b32 s13, s3, 8
	s_add_u32 s12, s12, s13
	s_add_u32 s30, s21, s12
	s_addc_u32 s31, s68, 0
	s_mul_i32 s12, s3, 0x58000
	s_lshl_b32 s13, s2, 8
	s_add_u32 s12, s12, s13
	s_add_u32 s74, s6, s12
	s_addc_u32 s75, s7, 0
	s_movk_i32 s76, 0x1000
	s_movk_i32 s86, 0x1600
	s_branch .Lptr_dec13_done

.Lptr_dec13_done:
	v_mul_lo_u32 v122, v116, s86
	v_add_u32_e32 v122, v122, v117
	s_waitcnt lgkmcnt(0)
	v_cvt_pk_bf16_f32 v104, v88, v89
	v_cvt_pk_bf16_f32 v105, v90, v91
	v_cvt_pk_bf16_f32 v106, v92, v93
	v_cvt_pk_bf16_f32 v107, v94, v95
	v_cvt_pk_bf16_f32 v108, v96, v97
	v_cvt_pk_bf16_f32 v109, v98, v99
	v_cvt_pk_bf16_f32 v110, v100, v101
	v_cvt_pk_bf16_f32 v111, v102, v103
	global_store_dwordx4 v122, v[104:107], s[74:75]
	global_store_dwordx4 v122, v[108:111], s[74:75] offset:16
	s_nop 1
	s_waitcnt vmcnt(4)
	ds_write_b32 v114, v40 offset:0
	ds_write_b32 v114, v41 offset:4
	ds_write_b32 v114, v42 offset:8
	ds_write_b32 v114, v43 offset:12
	ds_write_b32 v114, v44 offset:8320
	ds_write_b32 v114, v45 offset:8324
	ds_write_b32 v114, v46 offset:8328
	ds_write_b32 v114, v47 offset:8332
	ds_write_b32 v114, v48 offset:16640
	ds_write_b32 v114, v49 offset:16644
	ds_write_b32 v114, v50 offset:16648
	ds_write_b32 v114, v51 offset:16652
	ds_write_b32 v114, v52 offset:24960
	ds_write_b32 v114, v53 offset:24964
	ds_write_b32 v114, v54 offset:24968
	ds_write_b32 v114, v55 offset:24972
	s_waitcnt lgkmcnt(0)
	s_barrier
	ds_read_b32 v88, v115 offset:0
	ds_read_b32 v89, v115 offset:260
	ds_read_b32 v90, v115 offset:520
	ds_read_b32 v91, v115 offset:780
	ds_read_b32 v92, v115 offset:1040
	ds_read_b32 v93, v115 offset:1300
	ds_read_b32 v94, v115 offset:1560
	ds_read_b32 v95, v115 offset:1820
	ds_read_b32 v96, v115 offset:2080
	ds_read_b32 v97, v115 offset:2340
	ds_read_b32 v98, v115 offset:2600
	ds_read_b32 v99, v115 offset:2860
	ds_read_b32 v100, v115 offset:3120
	ds_read_b32 v101, v115 offset:3380
	ds_read_b32 v102, v115 offset:3640
	ds_read_b32 v103, v115 offset:3900
	s_mul_i32 s48, s81, 6
	s_add_u32 s48, s48, s39
	s_min_u32 s48, s48, s84
	s_sub_u32 s0, s48, 0x80
	s_cmpk_lt_u32 s0, 0x80
	s_cbranch_scc1 .Lptr_dec14_br
	s_cmpk_lt_u32 s0, 0x100
	s_cbranch_scc1 .Lptr_dec14_out
	s_cmpk_lt_u32 s0, 0x3c0
	s_cbranch_scc1 .Lptr_dec14_up
	s_sub_u32 s0, s0, 0x3c0
	s_lshr_b32 s2, s0, 4
	s_and_b32 s3, s0, 15
	s_lshl_b32 s12, s2, 19
	s_lshl_b32 s13, s3, 8
	s_add_u32 s12, s12, s13
	s_add_u32 s30, s21, s12
	s_addc_u32 s31, s68, 0
	s_mul_i32 s12, s3, 0x58000
	s_lshl_b32 s13, s2, 8
	s_add_u32 s12, s12, s13
	s_add_u32 s74, s6, s12
	s_addc_u32 s75, s7, 0
	s_movk_i32 s76, 0x1000
	s_movk_i32 s86, 0x1600
	s_branch .Lptr_dec14_done

.Lptr_dec14_done:
	v_mul_lo_u32 v122, v116, s86
	v_add_u32_e32 v122, v122, v117
	s_waitcnt lgkmcnt(0)
	v_cvt_pk_bf16_f32 v104, v88, v89
	v_cvt_pk_bf16_f32 v105, v90, v91
	v_cvt_pk_bf16_f32 v106, v92, v93
	v_cvt_pk_bf16_f32 v107, v94, v95
	v_cvt_pk_bf16_f32 v108, v96, v97
	v_cvt_pk_bf16_f32 v109, v98, v99
	v_cvt_pk_bf16_f32 v110, v100, v101
	v_cvt_pk_bf16_f32 v111, v102, v103
	global_store_dwordx4 v122, v[104:107], s[74:75]
	global_store_dwordx4 v122, v[108:111], s[74:75] offset:16
	s_nop 1
	s_waitcnt vmcnt(0)
	s_barrier
	s_branch .LBB0_602
